# prep: x to bf16 conversion as a software-pipelined loop (6 items in flight per thread), on top of the pipelined fp4 conversion
# baseline (speedup 1.0000x reference)
.Luv_done:
	v_lshlrev_b32_e32 v148, 5, v154
	v_lshlrev_b32_e32 v149, 4, v154
	s_mov_b32 s101, 0x6a00
	s_mov_b32 s98, s2
.Lxc_first:
	s_cmpk_ge_u32 s98, 0x4a00
	s_cbranch_scc1 .Lxc_first_ok
	s_add_u32 s98, s98, s33
	s_branch .Lxc_first
.Lxc_first_ok:
	s_mov_b32 s99, s98
	s_min_u32 s71, s99, 0x69ff
	s_sub_u32 s32, s71, 0x4a00
	v_readlane_b32 s96, v245, 5
	v_readlane_b32 s97, v245, 6
	s_lshl_b32 s32, s32, 13
	s_nop 0
	s_add_u32 s96, s96, s32
	s_addc_u32 s97, s97, 0
	s_nop 0
	global_load_dwordx4 v[192:195], v148, s[96:97]
	global_load_dwordx4 v[196:199], v148, s[96:97] offset:16
	s_add_u32 s99, s99, s33
	s_min_u32 s71, s99, 0x69ff
	s_sub_u32 s32, s71, 0x4a00
	v_readlane_b32 s96, v245, 5
	v_readlane_b32 s97, v245, 6
	s_lshl_b32 s32, s32, 13
	s_nop 0
	s_add_u32 s96, s96, s32
	s_addc_u32 s97, s97, 0
	s_nop 0
	global_load_dwordx4 v[200:203], v148, s[96:97]
	global_load_dwordx4 v[204:207], v148, s[96:97] offset:16
	s_add_u32 s99, s99, s33
	s_min_u32 s71, s99, 0x69ff
	s_sub_u32 s32, s71, 0x4a00
	v_readlane_b32 s96, v245, 5
	v_readlane_b32 s97, v245, 6
	s_lshl_b32 s32, s32, 13
	s_nop 0
	s_add_u32 s96, s96, s32
	s_addc_u32 s97, s97, 0
	s_nop 0
	global_load_dwordx4 v[208:211], v148, s[96:97]
	global_load_dwordx4 v[212:215], v148, s[96:97] offset:16
	s_add_u32 s99, s99, s33
	s_min_u32 s71, s99, 0x69ff
	s_sub_u32 s32, s71, 0x4a00
	v_readlane_b32 s96, v245, 5
	v_readlane_b32 s97, v245, 6
	s_lshl_b32 s32, s32, 13
	s_nop 0
	s_add_u32 s96, s96, s32
	s_addc_u32 s97, s97, 0
	s_nop 0
	global_load_dwordx4 v[216:219], v148, s[96:97]
	global_load_dwordx4 v[220:223], v148, s[96:97] offset:16
	s_add_u32 s99, s99, s33
	s_min_u32 s71, s99, 0x69ff
	s_sub_u32 s32, s71, 0x4a00
	v_readlane_b32 s96, v245, 5
	v_readlane_b32 s97, v245, 6
	s_lshl_b32 s32, s32, 13
	s_nop 0
	s_add_u32 s96, s96, s32
	s_addc_u32 s97, s97, 0
	s_nop 0
	global_load_dwordx4 v[224:227], v148, s[96:97]
	global_load_dwordx4 v[228:231], v148, s[96:97] offset:16
	s_add_u32 s99, s99, s33
	s_min_u32 s71, s99, 0x69ff
	s_sub_u32 s32, s71, 0x4a00
	v_readlane_b32 s96, v245, 5
	v_readlane_b32 s97, v245, 6
	s_lshl_b32 s32, s32, 13
	s_nop 0
	s_add_u32 s96, s96, s32
	s_addc_u32 s97, s97, 0
	s_nop 0
	global_load_dwordx4 v[232:235], v148, s[96:97]
	global_load_dwordx4 v[236:239], v148, s[96:97] offset:16
	s_add_u32 s99, s99, s33
	s_cmp_ge_u32 s98, s101
	s_cbranch_scc1 .Lxc_done
	s_waitcnt vmcnt(10)
	v_cvt_pk_bf16_f32 v192, v192, v193
	v_cvt_pk_bf16_f32 v193, v194, v195
	v_cvt_pk_bf16_f32 v194, v196, v197
	v_cvt_pk_bf16_f32 v195, v198, v199
	s_sub_u32 s32, s98, 0x4a00
	v_readlane_b32 s96, v245, 49
	v_readlane_b32 s97, v245, 50
	s_lshl_b32 s32, s32, 12
	s_nop 0
	s_add_u32 s96, s96, s32
	s_addc_u32 s97, s97, 0
	s_nop 0
	global_store_dwordx4 v149, v[192:195], s[96:97]
	s_add_u32 s98, s98, s33
	s_nop 0
	s_min_u32 s71, s99, 0x69ff
	s_sub_u32 s32, s71, 0x4a00
	v_readlane_b32 s96, v245, 5
	v_readlane_b32 s97, v245, 6
	s_lshl_b32 s32, s32, 13
	s_nop 0
	s_add_u32 s96, s96, s32
	s_addc_u32 s97, s97, 0
	s_nop 0
	global_load_dwordx4 v[192:195], v148, s[96:97]
	global_load_dwordx4 v[196:199], v148, s[96:97] offset:16
	s_add_u32 s99, s99, s33
	s_cmp_ge_u32 s98, s101
	s_cbranch_scc1 .Lxc_done
	s_waitcnt vmcnt(11)
	v_cvt_pk_bf16_f32 v200, v200, v201
	v_cvt_pk_bf16_f32 v201, v202, v203
	v_cvt_pk_bf16_f32 v202, v204, v205
	v_cvt_pk_bf16_f32 v203, v206, v207
	s_sub_u32 s32, s98, 0x4a00
	v_readlane_b32 s96, v245, 49
	v_readlane_b32 s97, v245, 50
	s_lshl_b32 s32, s32, 12
	s_nop 0
	s_add_u32 s96, s96, s32
	s_addc_u32 s97, s97, 0
	s_nop 0
	global_store_dwordx4 v149, v[200:203], s[96:97]
	s_add_u32 s98, s98, s33
	s_nop 0
	s_min_u32 s71, s99, 0x69ff
	s_sub_u32 s32, s71, 0x4a00
	v_readlane_b32 s96, v245, 5
	v_readlane_b32 s97, v245, 6
	s_lshl_b32 s32, s32, 13
	s_nop 0
	s_add_u32 s96, s96, s32
	s_addc_u32 s97, s97, 0
	s_nop 0
	global_load_dwordx4 v[200:203], v148, s[96:97]
	global_load_dwordx4 v[204:207], v148, s[96:97] offset:16
	s_add_u32 s99, s99, s33
	s_cmp_ge_u32 s98, s101
	s_cbranch_scc1 .Lxc_done
	s_waitcnt vmcnt(12)
	v_cvt_pk_bf16_f32 v208, v208, v209
	v_cvt_pk_bf16_f32 v209, v210, v211
	v_cvt_pk_bf16_f32 v210, v212, v213
	v_cvt_pk_bf16_f32 v211, v214, v215
	s_sub_u32 s32, s98, 0x4a00
	v_readlane_b32 s96, v245, 49
	v_readlane_b32 s97, v245, 50
	s_lshl_b32 s32, s32, 12
	s_nop 0
	s_add_u32 s96, s96, s32
	s_addc_u32 s97, s97, 0
	s_nop 0
	global_store_dwordx4 v149, v[208:211], s[96:97]
	s_add_u32 s98, s98, s33
	s_nop 0
	s_min_u32 s71, s99, 0x69ff
	s_sub_u32 s32, s71, 0x4a00
	v_readlane_b32 s96, v245, 5
	v_readlane_b32 s97, v245, 6
	s_lshl_b32 s32, s32, 13
	s_nop 0
	s_add_u32 s96, s96, s32
	s_addc_u32 s97, s97, 0
	s_nop 0
	global_load_dwordx4 v[208:211], v148, s[96:97]
	global_load_dwordx4 v[212:215], v148, s[96:97] offset:16
	s_add_u32 s99, s99, s33
	s_cmp_ge_u32 s98, s101
	s_cbranch_scc1 .Lxc_done
	s_waitcnt vmcnt(13)
	v_cvt_pk_bf16_f32 v216, v216, v217
	v_cvt_pk_bf16_f32 v217, v218, v219
	v_cvt_pk_bf16_f32 v218, v220, v221
	v_cvt_pk_bf16_f32 v219, v222, v223
	s_sub_u32 s32, s98, 0x4a00
	v_readlane_b32 s96, v245, 49
	v_readlane_b32 s97, v245, 50
	s_lshl_b32 s32, s32, 12
	s_nop 0
	s_add_u32 s96, s96, s32
	s_addc_u32 s97, s97, 0
	s_nop 0
	global_store_dwordx4 v149, v[216:219], s[96:97]
	s_add_u32 s98, s98, s33
	s_nop 0
	s_min_u32 s71, s99, 0x69ff
	s_sub_u32 s32, s71, 0x4a00
	v_readlane_b32 s96, v245, 5
	v_readlane_b32 s97, v245, 6
	s_lshl_b32 s32, s32, 13
	s_nop 0
	s_add_u32 s96, s96, s32
	s_addc_u32 s97, s97, 0
	s_nop 0
	global_load_dwordx4 v[216:219], v148, s[96:97]
	global_load_dwordx4 v[220:223], v148, s[96:97] offset:16
	s_add_u32 s99, s99, s33
	s_cmp_ge_u32 s98, s101
	s_cbranch_scc1 .Lxc_done
	s_waitcnt vmcnt(14)
	v_cvt_pk_bf16_f32 v224, v224, v225
	v_cvt_pk_bf16_f32 v225, v226, v227
	v_cvt_pk_bf16_f32 v226, v228, v229
	v_cvt_pk_bf16_f32 v227, v230, v231
	s_sub_u32 s32, s98, 0x4a00
	v_readlane_b32 s96, v245, 49
	v_readlane_b32 s97, v245, 50
	s_lshl_b32 s32, s32, 12
	s_nop 0
	s_add_u32 s96, s96, s32
	s_addc_u32 s97, s97, 0
	s_nop 0
	global_store_dwordx4 v149, v[224:227], s[96:97]
	s_add_u32 s98, s98, s33
	s_nop 0
	s_min_u32 s71, s99, 0x69ff
	s_sub_u32 s32, s71, 0x4a00
	v_readlane_b32 s96, v245, 5
	v_readlane_b32 s97, v245, 6
	s_lshl_b32 s32, s32, 13
	s_nop 0
	s_add_u32 s96, s96, s32
	s_addc_u32 s97, s97, 0
	s_nop 0
	global_load_dwordx4 v[224:227], v148, s[96:97]
	global_load_dwordx4 v[228:231], v148, s[96:97] offset:16
	s_add_u32 s99, s99, s33
	s_cmp_ge_u32 s98, s101
	s_cbranch_scc1 .Lxc_done
	s_waitcnt vmcnt(15)
	v_cvt_pk_bf16_f32 v232, v232, v233
	v_cvt_pk_bf16_f32 v233, v234, v235
	v_cvt_pk_bf16_f32 v234, v236, v237
	v_cvt_pk_bf16_f32 v235, v238, v239
	s_sub_u32 s32, s98, 0x4a00
	v_readlane_b32 s96, v245, 49
	v_readlane_b32 s97, v245, 50
	s_lshl_b32 s32, s32, 12
	s_nop 0
	s_add_u32 s96, s96, s32
	s_addc_u32 s97, s97, 0
	s_nop 0
	global_store_dwordx4 v149, v[232:235], s[96:97]
	s_add_u32 s98, s98, s33
	s_nop 0
	s_min_u32 s71, s99, 0x69ff
	s_sub_u32 s32, s71, 0x4a00
	v_readlane_b32 s96, v245, 5
	v_readlane_b32 s97, v245, 6
	s_lshl_b32 s32, s32, 13
	s_nop 0
	s_add_u32 s96, s96, s32
	s_addc_u32 s97, s97, 0
	s_nop 0
	global_load_dwordx4 v[232:235], v148, s[96:97]
	global_load_dwordx4 v[236:239], v148, s[96:97] offset:16
	s_add_u32 s99, s99, s33
.Lxc_loop:
	s_cmp_ge_u32 s98, s101
	s_cbranch_scc1 .Lxc_done
	s_waitcnt vmcnt(15)
	v_cvt_pk_bf16_f32 v192, v192, v193
	v_cvt_pk_bf16_f32 v193, v194, v195
	v_cvt_pk_bf16_f32 v194, v196, v197
	v_cvt_pk_bf16_f32 v195, v198, v199
	s_sub_u32 s32, s98, 0x4a00
	v_readlane_b32 s96, v245, 49
	v_readlane_b32 s97, v245, 50
	s_lshl_b32 s32, s32, 12
	s_nop 0
	s_add_u32 s96, s96, s32
	s_addc_u32 s97, s97, 0
	s_nop 0
	global_store_dwordx4 v149, v[192:195], s[96:97]
	s_add_u32 s98, s98, s33
	s_nop 0
	s_min_u32 s71, s99, 0x69ff
	s_sub_u32 s32, s71, 0x4a00
	v_readlane_b32 s96, v245, 5
	v_readlane_b32 s97, v245, 6
	s_lshl_b32 s32, s32, 13
	s_nop 0
	s_add_u32 s96, s96, s32
	s_addc_u32 s97, s97, 0
	s_nop 0
	global_load_dwordx4 v[192:195], v148, s[96:97]
	global_load_dwordx4 v[196:199], v148, s[96:97] offset:16
	s_add_u32 s99, s99, s33
	s_cmp_ge_u32 s98, s101
	s_cbranch_scc1 .Lxc_done
	s_waitcnt vmcnt(15)
	v_cvt_pk_bf16_f32 v200, v200, v201
	v_cvt_pk_bf16_f32 v201, v202, v203
	v_cvt_pk_bf16_f32 v202, v204, v205
	v_cvt_pk_bf16_f32 v203, v206, v207
	s_sub_u32 s32, s98, 0x4a00
	v_readlane_b32 s96, v245, 49
	v_readlane_b32 s97, v245, 50
	s_lshl_b32 s32, s32, 12
	s_nop 0
	s_add_u32 s96, s96, s32
	s_addc_u32 s97, s97, 0
	s_nop 0
	global_store_dwordx4 v149, v[200:203], s[96:97]
	s_add_u32 s98, s98, s33
	s_nop 0
	s_min_u32 s71, s99, 0x69ff
	s_sub_u32 s32, s71, 0x4a00
	v_readlane_b32 s96, v245, 5
	v_readlane_b32 s97, v245, 6
	s_lshl_b32 s32, s32, 13
	s_nop 0
	s_add_u32 s96, s96, s32
	s_addc_u32 s97, s97, 0
	s_nop 0
	global_load_dwordx4 v[200:203], v148, s[96:97]
	global_load_dwordx4 v[204:207], v148, s[96:97] offset:16
	s_add_u32 s99, s99, s33
	s_cmp_ge_u32 s98, s101
	s_cbranch_scc1 .Lxc_done
	s_waitcnt vmcnt(15)
	v_cvt_pk_bf16_f32 v208, v208, v209
	v_cvt_pk_bf16_f32 v209, v210, v211
	v_cvt_pk_bf16_f32 v210, v212, v213
	v_cvt_pk_bf16_f32 v211, v214, v215
	s_sub_u32 s32, s98, 0x4a00
	v_readlane_b32 s96, v245, 49
	v_readlane_b32 s97, v245, 50
	s_lshl_b32 s32, s32, 12
	s_nop 0
	s_add_u32 s96, s96, s32
	s_addc_u32 s97, s97, 0
	s_nop 0
	global_store_dwordx4 v149, v[208:211], s[96:97]
	s_add_u32 s98, s98, s33
	s_nop 0
	s_min_u32 s71, s99, 0x69ff
	s_sub_u32 s32, s71, 0x4a00
	v_readlane_b32 s96, v245, 5
	v_readlane_b32 s97, v245, 6
	s_lshl_b32 s32, s32, 13
	s_nop 0
	s_add_u32 s96, s96, s32
	s_addc_u32 s97, s97, 0
	s_nop 0
	global_load_dwordx4 v[208:211], v148, s[96:97]
	global_load_dwordx4 v[212:215], v148, s[96:97] offset:16
	s_add_u32 s99, s99, s33
	s_cmp_ge_u32 s98, s101
	s_cbranch_scc1 .Lxc_done
	s_waitcnt vmcnt(15)
	v_cvt_pk_bf16_f32 v216, v216, v217
	v_cvt_pk_bf16_f32 v217, v218, v219
	v_cvt_pk_bf16_f32 v218, v220, v221
	v_cvt_pk_bf16_f32 v219, v222, v223
	s_sub_u32 s32, s98, 0x4a00
	v_readlane_b32 s96, v245, 49
	v_readlane_b32 s97, v245, 50
	s_lshl_b32 s32, s32, 12
	s_nop 0
	s_add_u32 s96, s96, s32
	s_addc_u32 s97, s97, 0
	s_nop 0
	global_store_dwordx4 v149, v[216:219], s[96:97]
	s_add_u32 s98, s98, s33
	s_nop 0
	s_min_u32 s71, s99, 0x69ff
	s_sub_u32 s32, s71, 0x4a00
	v_readlane_b32 s96, v245, 5
	v_readlane_b32 s97, v245, 6
	s_lshl_b32 s32, s32, 13
	s_nop 0
	s_add_u32 s96, s96, s32
	s_addc_u32 s97, s97, 0
	s_nop 0
	global_load_dwordx4 v[216:219], v148, s[96:97]
	global_load_dwordx4 v[220:223], v148, s[96:97] offset:16
	s_add_u32 s99, s99, s33
	s_cmp_ge_u32 s98, s101
	s_cbranch_scc1 .Lxc_done
	s_waitcnt vmcnt(15)
	v_cvt_pk_bf16_f32 v224, v224, v225
	v_cvt_pk_bf16_f32 v225, v226, v227
	v_cvt_pk_bf16_f32 v226, v228, v229
	v_cvt_pk_bf16_f32 v227, v230, v231
	s_sub_u32 s32, s98, 0x4a00
	v_readlane_b32 s96, v245, 49
	v_readlane_b32 s97, v245, 50
	s_lshl_b32 s32, s32, 12
	s_nop 0
	s_add_u32 s96, s96, s32
	s_addc_u32 s97, s97, 0
	s_nop 0
	global_store_dwordx4 v149, v[224:227], s[96:97]
	s_add_u32 s98, s98, s33
	s_nop 0
	s_min_u32 s71, s99, 0x69ff
	s_sub_u32 s32, s71, 0x4a00
	v_readlane_b32 s96, v245, 5
	v_readlane_b32 s97, v245, 6
	s_lshl_b32 s32, s32, 13
	s_nop 0
	s_add_u32 s96, s96, s32
	s_addc_u32 s97, s97, 0
	s_nop 0
	global_load_dwordx4 v[224:227], v148, s[96:97]
	global_load_dwordx4 v[228:231], v148, s[96:97] offset:16
	s_add_u32 s99, s99, s33
	s_cmp_ge_u32 s98, s101
	s_cbranch_scc1 .Lxc_done
	s_waitcnt vmcnt(15)
	v_cvt_pk_bf16_f32 v232, v232, v233
	v_cvt_pk_bf16_f32 v233, v234, v235
	v_cvt_pk_bf16_f32 v234, v236, v237
	v_cvt_pk_bf16_f32 v235, v238, v239
	s_sub_u32 s32, s98, 0x4a00
	v_readlane_b32 s96, v245, 49
	v_readlane_b32 s97, v245, 50
	s_lshl_b32 s32, s32, 12
	s_nop 0
	s_add_u32 s96, s96, s32
	s_addc_u32 s97, s97, 0
	s_nop 0
	global_store_dwordx4 v149, v[232:235], s[96:97]
	s_add_u32 s98, s98, s33
	s_nop 0
	s_min_u32 s71, s99, 0x69ff
	s_sub_u32 s32, s71, 0x4a00
	v_readlane_b32 s96, v245, 5
	v_readlane_b32 s97, v245, 6
	s_lshl_b32 s32, s32, 13
	s_nop 0
	s_add_u32 s96, s96, s32
	s_addc_u32 s97, s97, 0
	s_nop 0
	global_load_dwordx4 v[232:235], v148, s[96:97]
	global_load_dwordx4 v[236:239], v148, s[96:97] offset:16
	s_add_u32 s99, s99, s33
	s_branch .Lxc_loop
